# MLA attention loop: one workgroup barrier per key tile instead of two (3-slot LDS ring makes the mid-step barrier unnecessary), no half-workgroup stagger
# speedup vs baseline: 1.0201x; 1.0051x over previous
; #define LAS __attribute__((address_space(3)))
; DI unsigned pk2(float lo, float hi) { f32x2_t v = {lo, hi}; bf16x2_t b = __builtin_convertvector(v, bf16x2_t); return __builtin_bit_cast(unsigned, b); }
; #define MFMA32(a, b, c) __builtin_amdgcn_mfma_f32_32x32x16_bf16((a), (b), (c), 0, 0, 0)
; template <int MODE> DI void attn_unit(int b, int qb, const bf16* Qb, int qpitch, const bf16* Kb, int kpitch, const bf16* VT, bf16* O, float* ssq, ...
;     ...
;             const LAS unsigned char* vb = lds + VOFF + buf * VSZ + r32 * 136 + 8 * hi;
; #pragma unroll
;             for (int s4 = 0; s4 < 4; ++s4) {
;                 v4u pw;
;                 if (s4 == 0) { pw.x = pk2(p0[0], p0[1]); pw.y = pk2(p0[2], p0[3]); pw.z = pk2(p0[4], p0[5]); pw.w = pk2(p0[6], p0[7]); }
;                 if (s4 == 1) { pw.x = pk2(p0[8], p0[9]); pw.y = pk2(p0[10], p0[11]); pw.z = pk2(p0[12], p0[13]); pw.w = pk2(p0[14], p0[15]); }
;                 if (s4 == 2) { pw.x = pk2(p1[0], p1[1]); pw.y = pk2(p1[2], p1[3]); pw.z = pk2(p1[4], p1[5]); pw.w = pk2(p1[6], p1[7]); }
;                 if (s4 == 3) { pw.x = pk2(p1[8], p1[9]); pw.y = pk2(p1[10], p1[11]); pw.z = pk2(p1[12], p1[13]); pw.w = pk2(p1[14], p1[15]); }
;                 const v8s pf = __builtin_bit_cast(v8s, pw);
;                 const v2u a0 = *(const LAS v2u*)(vb + 32 * s4), a1 = *(const LAS v2u*)(vb + 32 * s4 + 16);
;                 const v2u c0 = *(const LAS v2u*)(vb + 32 * 136 + 32 * s4), c1 = *(const LAS v2u*)(vb + 32 * 136 + 32 * s4 + 16);
;                 const v4u va = {a0.x, a0.y, a1.x, a1.y}, vc2 = {c0.x, c0.y, c1.x, c1.y};
;                 o0 = MFMA32(__builtin_bit_cast(v8s, va), pf, o0);
;                 o1 = MFMA32(__builtin_bit_cast(v8s, vc2), pf, o1);
;             }
.Lmla_nov_p:
.Lmla_loop:
	s_cmp_eq_u32 s101, 0
	s_cbranch_scc1 .Lmla_nopv
	s_lshr_b32 s24, s100, 8
	s_and_b32 s24, s24, 0xffffff00
	v_add_u32_e32 v41, s24, v195
	v_add_u32_e32 v62, 0x1000, v41
	ds_read2_b64 v[50:53], v41 offset1:2
	ds_read2_b64 v[54:57], v41 offset0:4 offset1:6
	ds_read2_b64 v[58:61], v62 offset0:32 offset1:34
	s_waitcnt lgkmcnt(2)
	v_mfma_f32_32x32x16_bf16 v[0:15], v[50:53], v[42:45], v[0:15]
	s_waitcnt lgkmcnt(0)
	v_mfma_f32_32x32x16_bf16 v[16:31], v[58:61], v[42:45], v[16:31]
	ds_read2_b64 v[42:45], v62 offset0:36 offset1:38
	v_mfma_f32_32x32x16_bf16 v[0:15], v[54:57], v[46:49], v[0:15]
	s_waitcnt lgkmcnt(0)
	v_mfma_f32_32x32x16_bf16 v[16:31], v[42:45], v[46:49], v[16:31]
	ds_read2_b64 v[42:45], v41 offset0:8 offset1:10
	ds_read2_b64 v[46:49], v62 offset0:40 offset1:42
	s_waitcnt lgkmcnt(1)
	v_mfma_f32_32x32x16_bf16 v[0:15], v[42:45], v[36:39], v[0:15]
	s_waitcnt lgkmcnt(0)
	v_mfma_f32_32x32x16_bf16 v[16:31], v[46:49], v[36:39], v[16:31]
	ds_read2_b64 v[36:39], v41 offset0:12 offset1:14
	ds_read2_b64 v[42:45], v62 offset0:44 offset1:46
	s_waitcnt lgkmcnt(1)
	v_mfma_f32_32x32x16_bf16 v[0:15], v[36:39], v[32:35], v[0:15]
	s_waitcnt lgkmcnt(0)
	v_mfma_f32_32x32x16_bf16 v[16:31], v[42:45], v[32:35], v[16:31]

; #define LAS __attribute__((address_space(3)))
; DI int crow(int r, int hi) { return (r & 3) + 8 * (r >> 2) + 4 * hi; }
; #define MFMA32(a, b, c) __builtin_amdgcn_mfma_f32_32x32x16_bf16((a), (b), (c), 0, 0, 0)
; template <int MODE> DI void attn_unit(int b, int qb, const bf16* Qb, int qpitch, const bf16* Kb, int kpitch, const bf16* VT, bf16* O, float* ssq, ...
;     ...
;         const bool active = (k0 <= qw0 + 31) && (MODE != 0 || k0 + 63 >= qw0 - 127);
;         if (active) {
;             const LAS unsigned char* kb = lds + KOFF + buf * KSZ + r32 * PK + 16 * hi;
;             v16f p0, p1;
; #pragma unroll
;             for (int d0 = 0; d0 < ND; ++d0) {
;                 const v8s ka = *(const LAS v8s*)(kb + 32 * d0), kb2 = *(const LAS v8s*)(kb + 32 * PK + 32 * d0);
;                 if (d0 == 0) { p0 = MFMA32(ka, qr[0], (v16f){}); p1 = MFMA32(kb2, qr[0], (v16f){}); }
;                 else { p0 = MFMA32(ka, qr[d0], p0); p1 = MFMA32(kb2, qr[d0], p1); }
;             }
;             asm volatile("s_nop 15\n\ts_nop 7" : "+v"(p0), "+v"(p1));
;             if (MODE == 1) {
;                 const LAS float* fb = (const LAS float*)(lds + FOFF + buf * 256);
; #pragma unroll
;                 for (int g = 0; g < 4; ++g) {
;                     const v4f f0 = *(const LAS v4f*)(fb + 8 * g + 4 * hi), f1 = *(const LAS v4f*)(fb + 32 + 8 * g + 4 * hi);
; #pragma unroll
;                     for (int i = 0; i < 4; ++i) { p0[4 * g + i] += f0[i]; p1[4 * g + i] += f1[i]; }
;                 }
;             }
;             if (MODE == 0) {
;                 const LAS float* tb = MS + (223 - q + k0 + 4 * hi);
; #pragma unroll
;                 for (int r = 0; r < 16; ++r) { p0[r] += tb[(r & 3) + 8 * (r >> 2)]; p1[r] += tb[32 + (r & 3) + 8 * (r >> 2)]; }
;             } else if (k0 + 63 > qw0) {
; #pragma unroll
;                 for (int r = 0; r < 16; ++r) {
;                     const int kv = k0 + crow(r, hi);
;                     if (kv > q) p0[r] = NEGBIG;
;                     if (kv + 32 > q) p1[r] = NEGBIG;
;                 }
;             }
.Lmla_noqk:
	s_cmp_gt_u32 s72, s61
	s_cbranch_scc1 .Lmla_inactive
	s_nop 7
	s_nop 3
	s_add_i32 s24, s72, 63
	s_cmp_le_u32 s24, s59
	s_cbranch_scc1 .LBB0_472
	v_add_u32_e32 v153, s72, v194
	v_add_u32_e32 v159, 32, v153
	v_cmp_le_u32_e32 vcc, v159, v64
	v_add_u32_e32 v159, 33, v153
	s_nop 6
	v_cndmask_b32_e32 v32, v234, v32, vcc
	v_cmp_lt_u32_e32 vcc, v153, v64
	s_nop 1
	v_cndmask_b32_e32 v49, v234, v49, vcc
	v_cmp_le_u32_e32 vcc, v153, v64
	s_nop 1
	v_cndmask_b32_e32 v48, v234, v48, vcc
	v_cmp_le_u32_e32 vcc, v159, v64
	v_add_u32_e32 v159, 2, v153
	s_nop 0
	v_cndmask_b32_e32 v33, v234, v33, vcc
	v_cmp_le_u32_e32 vcc, v159, v64
	v_add_u32_e32 v159, 34, v153
	s_nop 0
	v_cndmask_b32_e32 v50, v234, v50, vcc
	v_cmp_le_u32_e32 vcc, v159, v64
	v_add_u32_e32 v159, 3, v153
	s_nop 0
	v_cndmask_b32_e32 v34, v234, v34, vcc
	v_cmp_le_u32_e32 vcc, v159, v64
	v_add_u32_e32 v159, 35, v153
	s_nop 0
	v_cndmask_b32_e32 v51, v234, v51, vcc
	v_cmp_le_u32_e32 vcc, v159, v64
	v_add_u32_e32 v159, 8, v153
	s_nop 0
	v_cndmask_b32_e32 v35, v234, v35, vcc
	v_cmp_le_u32_e32 vcc, v159, v64
	v_add_u32_e32 v159, 40, v153
	s_nop 0
	v_cndmask_b32_e32 v52, v234, v52, vcc
	v_cmp_le_u32_e32 vcc, v159, v64
	v_add_u32_e32 v159, 9, v153
	s_nop 0
	v_cndmask_b32_e32 v36, v234, v36, vcc
	v_cmp_le_u32_e32 vcc, v159, v64
	v_add_u32_e32 v159, 41, v153
	s_nop 0
	v_cndmask_b32_e32 v53, v234, v53, vcc
	v_cmp_le_u32_e32 vcc, v159, v64
	v_add_u32_e32 v159, 10, v153
	s_nop 0
	v_cndmask_b32_e32 v37, v234, v37, vcc
	v_cmp_le_u32_e32 vcc, v159, v64
	v_add_u32_e32 v159, 42, v153
	s_nop 0
	v_cndmask_b32_e32 v54, v234, v54, vcc
	v_cmp_le_u32_e32 vcc, v159, v64
	v_add_u32_e32 v159, 11, v153
	s_nop 0
	v_cndmask_b32_e32 v38, v234, v38, vcc
	v_cmp_le_u32_e32 vcc, v159, v64
	v_add_u32_e32 v159, 43, v153
	s_nop 0
	v_cndmask_b32_e32 v55, v234, v55, vcc
	v_cmp_le_u32_e32 vcc, v159, v64
	v_add_u32_e32 v159, 16, v153
	s_nop 0
	v_cndmask_b32_e32 v39, v234, v39, vcc
	v_cmp_le_u32_e32 vcc, v159, v64
	v_add_u32_e32 v159, 48, v153
	s_nop 0
	v_cndmask_b32_e32 v56, v234, v56, vcc
	v_cmp_le_u32_e32 vcc, v159, v64
	v_add_u32_e32 v159, 17, v153
	s_nop 0
	v_cndmask_b32_e32 v40, v234, v40, vcc
	v_cmp_le_u32_e32 vcc, v159, v64
	v_add_u32_e32 v159, 49, v153
	s_nop 0
	v_cndmask_b32_e32 v57, v234, v57, vcc
	v_cmp_le_u32_e32 vcc, v159, v64
	v_add_u32_e32 v159, 18, v153
	s_nop 0
	v_cndmask_b32_e32 v41, v234, v41, vcc
	v_cmp_le_u32_e32 vcc, v159, v64
	v_add_u32_e32 v159, 50, v153
	s_nop 0
	v_cndmask_b32_e32 v58, v234, v58, vcc
	v_cmp_le_u32_e32 vcc, v159, v64
	v_add_u32_e32 v159, 19, v153
	s_nop 0
	v_cndmask_b32_e32 v42, v234, v42, vcc
	v_cmp_le_u32_e32 vcc, v159, v64
	v_add_u32_e32 v159, 51, v153
	s_nop 0
	v_cndmask_b32_e32 v59, v234, v59, vcc
	v_cmp_le_u32_e32 vcc, v159, v64
	v_add_u32_e32 v159, 24, v153
	s_nop 0
	v_cndmask_b32_e32 v43, v234, v43, vcc
	v_cmp_le_u32_e32 vcc, v159, v64
	v_add_u32_e32 v159, 56, v153
	s_nop 0
	v_cndmask_b32_e32 v60, v234, v60, vcc
	v_cmp_le_u32_e32 vcc, v159, v64
	v_add_u32_e32 v159, 25, v153
	s_nop 0
	v_cndmask_b32_e32 v44, v234, v44, vcc
	v_cmp_le_u32_e32 vcc, v159, v64
	v_add_u32_e32 v159, 57, v153
	s_nop 0
	v_cndmask_b32_e32 v61, v234, v61, vcc
	v_cmp_le_u32_e32 vcc, v159, v64
	v_add_u32_e32 v159, 26, v153
	s_nop 0
	v_cndmask_b32_e32 v45, v234, v45, vcc
	v_cmp_le_u32_e32 vcc, v159, v64
	v_add_u32_e32 v159, 58, v153
	s_nop 0
	v_cndmask_b32_e32 v62, v234, v62, vcc
	v_cmp_le_u32_e32 vcc, v159, v64
	v_add_u32_e32 v159, 27, v153
	v_add_u32_e32 v153, 59, v153
	v_cndmask_b32_e32 v46, v234, v46, vcc
	v_cmp_le_u32_e32 vcc, v159, v64
	s_nop 1
	v_cndmask_b32_e32 v63, v234, v63, vcc
	v_cmp_le_u32_e32 vcc, v153, v64
	s_nop 1
	v_cndmask_b32_e32 v47, v234, v47, vcc

; #define LAS __attribute__((address_space(3)))
; DI unsigned pk2(float lo, float hi) { f32x2_t v = {lo, hi}; bf16x2_t b = __builtin_convertvector(v, bf16x2_t); return __builtin_bit_cast(unsigned, b); }
; #define MFMA32(a, b, c) __builtin_amdgcn_mfma_f32_32x32x16_bf16((a), (b), (c), 0, 0, 0)
; template <int MODE> DI void attn_unit(int b, int qb, const bf16* Qb, int qpitch, const bf16* Kb, int kpitch, const bf16* VT, bf16* O, float* ssq, ...
;     ...
;             const LAS unsigned char* vb = lds + VOFF + buf * VSZ + r32 * 136 + 8 * hi;
; #pragma unroll
;             for (int s4 = 0; s4 < 4; ++s4) {
;                 v4u pw;
;                 if (s4 == 0) { pw.x = pk2(p0[0], p0[1]); pw.y = pk2(p0[2], p0[3]); pw.z = pk2(p0[4], p0[5]); pw.w = pk2(p0[6], p0[7]); }
;                 if (s4 == 1) { pw.x = pk2(p0[8], p0[9]); pw.y = pk2(p0[10], p0[11]); pw.z = pk2(p0[12], p0[13]); pw.w = pk2(p0[14], p0[15]); }
;                 if (s4 == 2) { pw.x = pk2(p1[0], p1[1]); pw.y = pk2(p1[2], p1[3]); pw.z = pk2(p1[4], p1[5]); pw.w = pk2(p1[6], p1[7]); }
;                 if (s4 == 3) { pw.x = pk2(p1[8], p1[9]); pw.y = pk2(p1[10], p1[11]); pw.z = pk2(p1[12], p1[13]); pw.w = pk2(p1[14], p1[15]); }
;                 const v8s pf = __builtin_bit_cast(v8s, pw);
;                 const v2u a0 = *(const LAS v2u*)(vb + 32 * s4), a1 = *(const LAS v2u*)(vb + 32 * s4 + 16);
;                 const v2u c0 = *(const LAS v2u*)(vb + 32 * 136 + 32 * s4), c1 = *(const LAS v2u*)(vb + 32 * 136 + 32 * s4 + 16);
;                 const v4u va = {a0.x, a0.y, a1.x, a1.y}, vc2 = {c0.x, c0.y, c1.x, c1.y};
;                 o0 = MFMA32(__builtin_bit_cast(v8s, va), pf, o0);
;                 o1 = MFMA32(__builtin_bit_cast(v8s, vc2), pf, o1);
;             }
;     ...
;     lsum += __shfl_xor(lsum, 32);
;     const float inv = 1.0f / lsum;
;     float sq = 0.f;
; #pragma unroll
;     for (int r = 0; r < 16; ++r) { o0[r] *= inv; o1[r] *= inv; sq += o0[r] * o0[r] + o1[r] * o1[r]; }
;     sq += __shfl_xor(sq, 32);
;     if (hi == 0) ssq[(rowbase + q) * 16] = sq;
.Lmla_nov_e:
	s_cmp_eq_u32 s69, s72
	s_waitcnt lgkmcnt(0)
	s_barrier
	s_cbranch_scc0 .Lmla_loop
	s_cmp_eq_u32 s101, 0
	s_cbranch_scc1 .Lmla_nopv2
	s_lshr_b32 s24, s100, 8
	s_and_b32 s24, s24, 0xffffff00
	v_add_u32_e32 v41, s24, v195
	v_add_u32_e32 v62, 0x1000, v41
	ds_read2_b64 v[50:53], v41 offset1:2
	ds_read2_b64 v[54:57], v41 offset0:4 offset1:6
	ds_read2_b64 v[58:61], v62 offset0:32 offset1:34
	s_waitcnt lgkmcnt(2)
	v_mfma_f32_32x32x16_bf16 v[0:15], v[50:53], v[42:45], v[0:15]
	s_waitcnt lgkmcnt(0)
	v_mfma_f32_32x32x16_bf16 v[16:31], v[58:61], v[42:45], v[16:31]
	ds_read2_b64 v[42:45], v62 offset0:36 offset1:38
	v_mfma_f32_32x32x16_bf16 v[0:15], v[54:57], v[46:49], v[0:15]
	s_waitcnt lgkmcnt(0)
	v_mfma_f32_32x32x16_bf16 v[16:31], v[42:45], v[46:49], v[16:31]
	ds_read2_b64 v[42:45], v41 offset0:8 offset1:10
	ds_read2_b64 v[46:49], v62 offset0:40 offset1:42
	s_waitcnt lgkmcnt(1)
	v_mfma_f32_32x32x16_bf16 v[0:15], v[42:45], v[36:39], v[0:15]
	s_waitcnt lgkmcnt(0)
	v_mfma_f32_32x32x16_bf16 v[16:31], v[46:49], v[36:39], v[16:31]
	ds_read2_b64 v[36:39], v41 offset0:12 offset1:14
	ds_read2_b64 v[42:45], v62 offset0:44 offset1:46
	s_waitcnt lgkmcnt(1)
	v_mfma_f32_32x32x16_bf16 v[0:15], v[36:39], v[32:35], v[0:15]
	s_waitcnt lgkmcnt(0)
	v_mfma_f32_32x32x16_bf16 v[16:31], v[42:45], v[32:35], v[16:31]
	s_nop 7
	s_nop 3
.Lmla_nopv2:
.LBB0_477:
	v_and_b32_e32 v36, 64, v226
	v_xor_b32_e32 v32, 32, v226
	v_add_u32_e32 v33, 64, v36
	v_cmp_lt_i32_e32 vcc, v32, v33
	s_nop 1
	v_cndmask_b32_e32 v32, v226, v32, vcc
	v_lshlrev_b32_e32 v190, 2, v32
	ds_bpermute_b32 v32, v190, v155
	s_waitcnt lgkmcnt(0)
	v_add_f32_e32 v32, v155, v32
	v_div_scale_f32 v33, s[22:23], v32, v32, 1.0
	v_rcp_f32_e32 v34, v33
	v_div_scale_f32 v35, vcc, 1.0, v32, 1.0
	v_fma_f32 v37, -v33, v34, 1.0
	v_fmac_f32_e32 v34, v37, v34
	v_mul_f32_e32 v37, v35, v34
	v_fma_f32 v38, -v33, v37, v35
	v_fmac_f32_e32 v37, v38, v34
	v_fma_f32 v33, -v33, v37, v35
	v_div_fmas_f32 v33, v33, v34, v37
	v_div_fixup_f32 v38, v33, v32, 1.0
	v_pk_mul_f32 v[32:33], v[0:1], v[38:39] op_sel_hi:[1,0]
	v_pk_mul_f32 v[0:1], v[16:17], v[38:39] op_sel_hi:[1,0]
	v_pk_mul_f32 v[16:17], v[32:33], v[32:33]
	v_pk_mul_f32 v[2:3], v[2:3], v[38:39] op_sel_hi:[1,0]
	v_pk_fma_f32 v[40:41], v[0:1], v[0:1], v[16:17]
	v_pk_mul_f32 v[34:35], v[2:3], v[2:3]
	v_pk_mul_f32 v[16:17], v[18:19], v[38:39] op_sel_hi:[1,0]
	v_pk_mul_f32 v[18:19], v[4:5], v[38:39] op_sel_hi:[1,0]
	v_pk_fma_f32 v[42:43], v[16:17], v[16:17], v[34:35]
	v_add_f32_e32 v37, v40, v41
	v_pk_mul_f32 v[34:35], v[18:19], v[18:19]
	v_pk_mul_f32 v[4:5], v[20:21], v[38:39] op_sel_hi:[1,0]
	v_add_f32_e32 v37, v42, v37
	v_pk_fma_f32 v[44:45], v[4:5], v[4:5], v[34:35]
	v_pk_mul_f32 v[34:35], v[6:7], v[38:39] op_sel_hi:[1,0]
	v_add_f32_e32 v37, v43, v37
	v_pk_mul_f32 v[20:21], v[34:35], v[34:35]
	v_pk_mul_f32 v[6:7], v[22:23], v[38:39] op_sel_hi:[1,0]
	v_add_f32_e32 v37, v44, v37
	v_pk_fma_f32 v[46:47], v[6:7], v[6:7], v[20:21]
	v_pk_mul_f32 v[8:9], v[8:9], v[38:39] op_sel_hi:[1,0]
	v_add_f32_e32 v37, v45, v37
	v_pk_mul_f32 v[22:23], v[8:9], v[8:9]
	v_pk_mul_f32 v[20:21], v[24:25], v[38:39] op_sel_hi:[1,0]
	v_add_f32_e32 v37, v46, v37
	v_pk_fma_f32 v[48:49], v[20:21], v[20:21], v[22:23]
	v_pk_mul_f32 v[10:11], v[10:11], v[38:39] op_sel_hi:[1,0]
	v_add_f32_e32 v37, v47, v37
	v_pk_mul_f32 v[24:25], v[10:11], v[10:11]
	v_pk_mul_f32 v[22:23], v[26:27], v[38:39] op_sel_hi:[1,0]
	v_add_f32_e32 v37, v48, v37
	v_pk_fma_f32 v[50:51], v[22:23], v[22:23], v[24:25]
	v_pk_mul_f32 v[24:25], v[12:13], v[38:39] op_sel_hi:[1,0]
	v_add_f32_e32 v37, v49, v37
	v_pk_mul_f32 v[26:27], v[24:25], v[24:25]
	v_pk_mul_f32 v[12:13], v[28:29], v[38:39] op_sel_hi:[1,0]
	v_add_f32_e32 v37, v50, v37
	v_pk_fma_f32 v[28:29], v[12:13], v[12:13], v[26:27]
	v_pk_mul_f32 v[26:27], v[14:15], v[38:39] op_sel_hi:[1,0]
	v_add_f32_e32 v37, v51, v37
	v_pk_mul_f32 v[52:53], v[26:27], v[26:27]
	v_pk_mul_f32 v[14:15], v[30:31], v[38:39] op_sel_hi:[1,0]
	v_add_f32_e32 v28, v28, v37
	v_pk_fma_f32 v[30:31], v[14:15], v[14:15], v[52:53]
	v_add_f32_e32 v28, v29, v28
	v_add_f32_e32 v28, v30, v28
	v_add_f32_e32 v28, v31, v28
	ds_bpermute_b32 v29, v190, v28
	s_and_saveexec_b64 s[22:23], s[56:57]
	s_cbranch_execz .LBB0_456
	v_lshlrev_b64 v[30:31], 6, v[182:183]
	v_lshl_add_u64 v[30:31], s[16:17], 0, v[30:31]
	s_waitcnt lgkmcnt(0)
	v_add_f32_e32 v28, v28, v29
	global_store_dword v[30:31], v28, off
	s_branch .LBB0_456
